# rstd LDS cache, cached path without the pre-store vmcnt(0) (vmcnt retires in strict issue order, reads and writes mixed, so the K loop's counted waits stay valid with epilogue stores queued behind the
# baseline (speedup 1.0000x reference)
; __device__ __forceinline__ unsigned cvt_pk_bf16(float lo, float hi) { unsigned r; asm volatile("v_cvt_pk_bf16_f32 %0, %1, %2" : "=v"(r) : "v"(lo), "v"(hi)); return r; }
;     __device__ __forceinline__ void operator()(const f32x4 (&acc)[2][2][4][2], const Unit& u, int wr, int wc, int fr, int fq) const {
;     ...
; #pragma unroll
;         for (int ai = 0; ai < 2; ++ai)
; #pragma unroll
;             for (int m = 0; m < 4; ++m) {
;                 const int row = row0 + ai * HALF + m * 16;
;                 const float rs = rsv[ai][m];
;                 bf16_t* rowp = O + (size_t)row * ldc + col0;
; #pragma unroll
;                 for (int bj = 0; bj < 2; ++bj) {
;                     const f32x4 v0 = acc[ai][bj][m][0] * rs, v1 = acc[ai][bj][m][1] * rs;
;                     u32x4 w; w.x = cvt_pk_bf16(v0[0], v0[1]); w.y = cvt_pk_bf16(v0[2], v0[3]); w.z = cvt_pk_bf16(v1[0], v1[1]); w.w = cvt_pk_bf16(v1[2], v1[3]);
;                     *(u32x4*)(rowp + bj * HALF) = w;
.Lmy_rs_cached_1:
	v_lshlrev_b32_e32 v210, 2, v1
	v_add_u32_e32 v210, 0x21000, v210
	ds_read_b32 v180, v210
	ds_read_b32 v184, v210 offset:64
	ds_read_b32 v188, v210 offset:128
	ds_read_b32 v192, v210 offset:192
	ds_read_b32 v196, v210 offset:512
	ds_read_b32 v200, v210 offset:576
	ds_read_b32 v204, v210 offset:640
	ds_read_b32 v208, v210 offset:704
	s_waitcnt lgkmcnt(0)
	v_lshl_add_u32 v162, s55, 8, v1
	v_ashrrev_i32_e32 v163, 31, v162
	v_lshlrev_b64 v[130:131], 6, v[162:163]
	v_lshl_add_u64 v[130:131], v[142:143], 0, v[130:131]
	v_or_b32_e32 v164, 16, v162
	v_ashrrev_i32_e32 v165, 31, v164
	v_or_b32_e32 v166, 32, v162
	v_ashrrev_i32_e32 v167, 31, v166
	v_or_b32_e32 v168, 48, v162
	v_ashrrev_i32_e32 v169, 31, v168
	v_add_u32_e32 v170, 0x80, v162
	v_ashrrev_i32_e32 v171, 31, v170
	v_add_u32_e32 v172, 0x90, v162
	v_ashrrev_i32_e32 v173, 31, v172
	v_add_u32_e32 v174, 0xa0, v162
	v_ashrrev_i32_e32 v175, 31, v174
	v_add_u32_e32 v176, 0xb0, v162
	v_ashrrev_i32_e32 v177, 31, v176
	v_mad_i64_i32 v[162:163], s[26:27], v162, s30, 0
	v_lshl_add_u64 v[162:163], v[162:163], 1, s[18:19]
	s_and_b64 vcc, exec, s[4:5]
	v_mov_b32_e32 v154, v131
	v_mov_b32_e32 v155, v132
	s_nop 0
	s_nop 1
	s_waitcnt lgkmcnt(0)
	s_nop 1
	s_waitcnt lgkmcnt(0)
	v_mov_b32_e32 v148, v180
	s_nop 1
	v_pk_mul_f32 v[128:129], v[128:129], v[148:149] op_sel_hi:[1,0]
	v_pk_mul_f32 v[126:127], v[126:127], v[148:149] op_sel_hi:[1,0]
	v_pk_mul_f32 v[120:121], v[120:121], v[148:149] op_sel_hi:[1,0]
	v_pk_mul_f32 v[118:119], v[118:119], v[148:149] op_sel_hi:[1,0]
	s_nop 0
	s_nop 1
	s_waitcnt lgkmcnt(0)
	s_nop 1
	s_waitcnt lgkmcnt(0)
	v_mov_b32_e32 v150, v184
	s_nop 1
	v_pk_mul_f32 v[112:113], v[112:113], v[150:151] op_sel_hi:[1,0]
	v_pk_mul_f32 v[110:111], v[110:111], v[150:151] op_sel_hi:[1,0]
	v_pk_mul_f32 v[104:105], v[104:105], v[150:151] op_sel_hi:[1,0]
	v_pk_mul_f32 v[102:103], v[102:103], v[150:151] op_sel_hi:[1,0]
	s_nop 0
	s_nop 1
	s_waitcnt lgkmcnt(0)
	s_nop 1
	s_waitcnt lgkmcnt(0)
	v_mov_b32_e32 v152, v188
	s_nop 1
	v_pk_mul_f32 v[96:97], v[96:97], v[152:153] op_sel_hi:[1,0]
	v_pk_mul_f32 v[94:95], v[94:95], v[152:153] op_sel_hi:[1,0]
	v_pk_mul_f32 v[88:89], v[88:89], v[152:153] op_sel_hi:[1,0]
	v_pk_mul_f32 v[86:87], v[86:87], v[152:153] op_sel_hi:[1,0]
	s_nop 0
	s_nop 1
	s_waitcnt lgkmcnt(0)
	s_nop 1
	s_waitcnt lgkmcnt(0)
	v_mov_b32_e32 v154, v192
	s_nop 1
	v_pk_mul_f32 v[80:81], v[80:81], v[154:155] op_sel_hi:[1,0]
	v_pk_mul_f32 v[78:79], v[78:79], v[154:155] op_sel_hi:[1,0]
	v_pk_mul_f32 v[72:73], v[72:73], v[154:155] op_sel_hi:[1,0]
	v_pk_mul_f32 v[70:71], v[70:71], v[154:155] op_sel_hi:[1,0]
	s_nop 0
	s_nop 1
	s_waitcnt lgkmcnt(0)
	s_nop 1
	s_waitcnt lgkmcnt(0)
	v_mov_b32_e32 v156, v196
	s_nop 1
	v_pk_mul_f32 v[64:65], v[64:65], v[156:157] op_sel_hi:[1,0]
	v_pk_mul_f32 v[62:63], v[62:63], v[156:157] op_sel_hi:[1,0]
	v_pk_mul_f32 v[56:57], v[56:57], v[156:157] op_sel_hi:[1,0]
	v_pk_mul_f32 v[54:55], v[54:55], v[156:157] op_sel_hi:[1,0]
	s_nop 0
	s_nop 1
	s_waitcnt lgkmcnt(0)
	s_nop 1
	s_waitcnt lgkmcnt(0)
	v_mov_b32_e32 v158, v200
	s_nop 1
	v_pk_mul_f32 v[48:49], v[48:49], v[158:159] op_sel_hi:[1,0]
	v_pk_mul_f32 v[46:47], v[46:47], v[158:159] op_sel_hi:[1,0]
	v_pk_mul_f32 v[40:41], v[40:41], v[158:159] op_sel_hi:[1,0]
	v_pk_mul_f32 v[38:39], v[38:39], v[158:159] op_sel_hi:[1,0]
	s_nop 0
	s_nop 1
	s_waitcnt lgkmcnt(0)
	s_nop 1
	s_waitcnt lgkmcnt(0)
	v_mov_b32_e32 v160, v204
	s_nop 1
	v_mov_b32_e32 v130, v204
	v_mov_b32_e32 v131, v205
	v_mov_b32_e32 v132, v206
	v_mov_b32_e32 v133, v207
	v_pk_mul_f32 v[32:33], v[32:33], v[160:161] op_sel_hi:[1,0]
	v_pk_mul_f32 v[30:31], v[30:31], v[160:161] op_sel_hi:[1,0]
	v_pk_mul_f32 v[24:25], v[24:25], v[160:161] op_sel_hi:[1,0]
	v_pk_mul_f32 v[22:23], v[22:23], v[160:161] op_sel_hi:[1,0]
	v_mov_b32_e32 v179, v132
	v_lshl_or_b32 v132, s54, 8, v151
	v_mov_b32_e32 v178, v131
	v_ashrrev_i32_e32 v133, 31, v132
	v_lshlrev_b64 v[132:133], 1, v[132:133]
	v_lshl_add_u64 v[162:163], v[162:163], 0, v[132:133]
	v_pk_mul_f32 v[178:179], v[124:125], v[148:149] op_sel_hi:[1,0]
	v_pk_mul_f32 v[124:125], v[122:123], v[148:149] op_sel_hi:[1,0]
	v_cvt_pk_bf16_f32 v122, v126, v127
	v_cvt_pk_bf16_f32 v123, v128, v129
	v_cvt_pk_bf16_f32 v124, v124, v125
	v_cvt_pk_bf16_f32 v125, v178, v179
	global_store_dwordx4 v[162:163], v[122:125], off
	s_nop 1
	s_nop 1
	s_nop 1
	s_waitcnt lgkmcnt(0)
	v_pk_mul_f32 v[122:123], v[116:117], v[148:149] op_sel_hi:[1,0]
	v_pk_mul_f32 v[116:117], v[114:115], v[148:149] op_sel_hi:[1,0]
	v_cvt_pk_bf16_f32 v114, v118, v119
	v_cvt_pk_bf16_f32 v115, v120, v121
	s_nop 1
	v_cvt_pk_bf16_f32 v116, v116, v117
	v_cvt_pk_bf16_f32 v117, v122, v123
	global_store_dwordx4 v[162:163], v[114:117], off offset:256
	s_waitcnt lgkmcnt(0)
	s_nop 1
	v_mad_i64_i32 v[114:115], s[26:27], v164, s30, 0
	v_lshl_add_u64 v[114:115], v[114:115], 1, s[18:19]
	v_lshl_add_u64 v[114:115], v[114:115], 0, v[132:133]
	v_pk_mul_f32 v[116:117], v[108:109], v[150:151] op_sel_hi:[1,0]
	v_pk_mul_f32 v[108:109], v[106:107], v[150:151] op_sel_hi:[1,0]
	v_cvt_pk_bf16_f32 v106, v110, v111
	v_cvt_pk_bf16_f32 v107, v112, v113
	v_cvt_pk_bf16_f32 v108, v108, v109
	v_cvt_pk_bf16_f32 v109, v116, v117
	global_store_dwordx4 v[114:115], v[106:109], off
	v_mov_b32_e32 v130, v208
